# attention block prologue: combined wait relaxed to vmcnt(2) (V pieces may stay in flight as in the original) and the store-ack wait at block start removed; on top of v50
# speedup vs baseline: 1.0023x; 1.0023x over previous
.LBB0_613:
	s_and_b64 s[0:1], s[88:89], exec
	v_readlane_b32 s0, v252, 21
	v_readlane_b32 s1, v252, 25
	s_cselect_b32 s92, s0, s1
	v_readlane_b32 s0, v252, 13
	v_readlane_b32 s1, v252, 14
	s_add_i32 s82, s92, s0
	v_readlane_b32 s0, v252, 62
	v_readlane_b32 s1, v252, 63
	s_or_b32 s74, s92, s78
	s_lshr_b32 s81, s92, 6
	s_and_b64 vcc, exec, s[0:1]
	s_mov_b64 s[2:3], -1
	s_cbranch_vccz .LBB0_796
	v_mbcnt_lo_u32_b32 v190, -1, 0
	v_mbcnt_hi_u32_b32 v190, -1, v190
	v_readlane_b32 s0, v252, 17
	v_and_b32_e32 v189, 63, v190
	v_lshlrev_b32_e32 v42, 4, v189
	v_or_b32_e32 v0, s0, v42
	s_mov_b32 s0, 0x51eb851f
	v_mul_hi_i32 v2, v0, s0
	v_lshrrev_b32_e32 v3, 31, v2
	v_ashrrev_i32_e32 v2, 7, v2
	v_add_u32_e32 v2, v2, v3
	v_and_b32_e32 v35, 63, v2
	v_mul_i32_i24_e32 v2, 0x190, v2
	v_sub_u32_e32 v2, v0, v2
	s_movk_i32 s1, 0x180
	v_ashrrev_i32_e32 v3, 4, v2
	v_cmp_gt_i32_e32 vcc, s1, v2
	v_readlane_b32 s2, v251, 49
	v_lshlrev_b32_e32 v43, 3, v189
	v_cndmask_b32_e32 v2, 0, v3, vcc
	v_cmp_lt_i32_e32 vcc, 15, v2
	v_mov_b32_e32 v4, s2
	v_or_b32_e32 v3, s78, v35
	v_cndmask_b32_e32 v5, v4, v181, vcc
	v_cndmask_b32_e64 v198, 12, 7, vcc
	v_lshl_add_u32 v200, v2, 4, v5
	v_add_u32_e32 v2, 0x2000, v0
	v_lshl_add_u32 v11, v3, v198, v200
	v_mul_hi_i32 v3, v2, s0
	v_lshrrev_b32_e32 v5, 31, v3
	v_ashrrev_i32_e32 v3, 7, v3
	v_add_u32_e32 v3, v3, v5
	v_and_b32_e32 v36, 63, v3
	v_mul_i32_i24_e32 v3, 0x190, v3
	v_sub_u32_e32 v2, v2, v3
	v_cndmask_b32_e32 v10, v248, v236, vcc
	v_ashrrev_i32_e32 v3, 4, v2
	v_cmp_gt_i32_e32 vcc, s1, v2
	v_add_u32_e32 v0, 0x4000, v0
	v_and_b32_e32 v39, 32, v190
	v_cndmask_b32_e32 v2, 0, v3, vcc
	v_cmp_lt_i32_e32 vcc, 15, v2
	v_and_b32_e32 v40, 24, v43
	v_bfe_u32 v191, v190, 5, 1
	v_cndmask_b32_e32 v3, v4, v181, vcc
	v_lshl_add_u32 v202, v2, 4, v3
	v_mul_hi_i32 v2, v0, s0
	v_lshrrev_b32_e32 v3, 31, v2
	v_ashrrev_i32_e32 v2, 7, v2
	v_add_u32_e32 v2, v2, v3
	v_and_b32_e32 v37, 63, v2
	v_mul_i32_i24_e32 v2, 0x190, v2
	v_sub_u32_e32 v0, v0, v2
	v_cndmask_b32_e64 v201, 12, 7, vcc
	v_cndmask_b32_e32 v12, v248, v236, vcc
	v_ashrrev_i32_e32 v2, 4, v0
	v_cmp_gt_i32_e32 vcc, s1, v0
	v_readlane_b32 s0, v250, 63
	v_and_b32_e32 v192, 31, v190
	v_cndmask_b32_e32 v0, 0, v2, vcc
	v_cmp_lt_i32_e32 vcc, 15, v0
	v_lshlrev_b32_e32 v34, 2, v191
	v_or_b32_e32 v5, s78, v36
	v_cndmask_b32_e32 v2, v4, v181, vcc
	v_lshl_add_u32 v204, v0, 4, v2
	v_add_u32_e32 v0, s0, v190
	v_bfe_u32 v38, v0, 2, 2
	v_lshrrev_b32_e32 v0, 1, v0
	v_and_b32_e32 v41, 8, v0
	v_readlane_b32 s0, v252, 1
	v_cndmask_b32_e64 v203, 12, 7, vcc
	v_or_b32_e32 v3, s78, v37
	v_or3_b32 v0, v38, s0, v41
	v_lshl_or_b32 v0, v0, 11, v39
	v_or3_b32 v0, v0, s72, v40
	v_or_b32_e32 v2, s82, v192
	v_lshlrev_b32_e32 v16, 1, v0
	v_lshl_add_u32 v13, v5, v201, v202
	v_cndmask_b32_e32 v14, v248, v236, vcc
	v_lshl_add_u32 v15, v3, v203, v204
	v_sub_u32_e32 v196, v2, v34
	v_add_u32_e32 v17, 0x1f700000, v16
	v_add_u32_e32 v18, 0x1f700080, v16
	v_add_u32_e32 v188, s70, v42
	s_setprio 1
	s_ashr_i32 s75, s74, 31
	s_lshl_b64 s[76:77], s[74:75], 12
	v_readlane_b32 s0, v252, 28
	v_readlane_b32 s2, v252, 13
	s_add_u32 s0, s0, s76
	v_readlane_b32 s1, v252, 31
	v_or_b32_e32 v0, s2, v192
	s_addc_u32 s1, s1, s77
	v_lshlrev_b64 v[2:3], 12, v[0:1]
	v_readlane_b32 s3, v252, 14
	v_lshl_add_u64 v[2:3], s[0:1], 0, v[2:3]
	s_lshl_b64 s[0:1], s[74:75], 11
	v_readlane_b32 s2, v252, 34
	v_lshlrev_b32_e32 v6, 4, v191
	v_mov_b32_e32 v7, v1
	s_add_u32 s2, s2, s0
	v_readlane_b32 s3, v252, 37
	v_lshl_add_u64 v[2:3], v[2:3], 0, v[6:7]
	v_lshlrev_b64 v[8:9], 11, v[0:1]
	s_addc_u32 s3, s3, s1
	flat_load_dwordx4 v[172:175], v[2:3]
	flat_load_dwordx4 v[168:171], v[2:3] offset:32
	flat_load_dwordx4 v[164:167], v[2:3] offset:64
	flat_load_dwordx4 v[160:163], v[2:3] offset:96
	flat_load_dwordx4 v[156:159], v[2:3] offset:128
	flat_load_dwordx4 v[152:155], v[2:3] offset:160
	flat_load_dwordx4 v[148:151], v[2:3] offset:192
	flat_load_dwordx4 v[144:147], v[2:3] offset:224
	v_lshl_add_u64 v[2:3], s[2:3], 0, v[8:9]
	v_lshl_add_u64 v[2:3], v[2:3], 0, v[6:7]
	flat_load_dwordx4 v[2:5], v[2:3]
	v_readlane_b32 s2, v252, 40
	s_add_u32 s0, s2, s0
	v_readlane_b32 s2, v252, 43
	s_addc_u32 s1, s2, s1
	v_add_u32_e32 v0, v11, v10
	s_cmp_lg_u32 0, -1
	v_lshl_add_u64 v[20:21], s[0:1], 0, v[8:9]
	v_lshl_add_u64 v[20:21], v[20:21], 0, v[6:7]
	s_mov_b32 s0, 0x29900000
	v_add_co_u32_e32 v8, vcc, s0, v20
	v_readlane_b32 s0, v250, 45
	s_nop 0
	v_addc_co_u32_e32 v9, vcc, 0, v21, vcc
	flat_load_dwordx4 v[24:27], v[8:9] offset:32
	flat_load_dwordx4 v[28:31], v[8:9] offset:64
	flat_load_dwordx4 v[44:47], v[8:9] offset:96
	s_mov_b32 m0, s0
	s_nop 0
	global_load_lds_dwordx4 v11, s[68:69]
	v_readlane_b32 s0, v251, 43
	s_mov_b32 m0, s0
	s_nop 0
	global_load_lds_dwordx4 v13, s[68:69]
	v_readlane_b32 s0, v253, 4
	s_mov_b32 m0, s33
	s_nop 0
	global_load_lds_dwordx4 v15, s[68:69]
	s_nop 0
	s_mov_b32 m0, s85
	s_nop 0
	global_load_lds_dwordx4 v17, s[68:69]
	s_nop 0
	s_mov_b32 m0, s0
	s_nop 0
	global_load_lds_dwordx4 v18, s[68:69]
	s_waitcnt vmcnt(2) lgkmcnt(0)
	ds_write_b128 v188, v[2:5]
	ds_write_b128 v188, v[24:27] offset:1024
	ds_write_b128 v188, v[28:31] offset:2048
	ds_write_b128 v188, v[44:47] offset:3072
	v_readlane_b32 s0, v251, 45
	s_waitcnt vmcnt(2)
	s_waitcnt lgkmcnt(0)
	s_barrier
	s_mov_b32 m0, s0
	s_nop 0
	global_load_lds_dwordx4 v0, s[68:69]
	v_readlane_b32 s0, v252, 9
	v_add_u32_e32 v0, v13, v12
	s_mov_b32 m0, s0
	s_nop 0
	global_load_lds_dwordx4 v0, s[68:69]
	v_readlane_b32 s0, v251, 47
	v_add_u32_e32 v0, v15, v14
	s_mov_b32 m0, s0
	s_nop 0
	global_load_lds_dwordx4 v0, s[68:69]
	v_readlane_b32 s0, v253, 7
	v_add_u32_e32 v0, 0x1f740000, v16
	s_mov_b32 m0, s0
	s_nop 0
	global_load_lds_dwordx4 v0, s[68:69]
	v_readlane_b32 s0, v253, 10
	v_add_u32_e32 v0, 0x1f740080, v16
	s_mov_b32 m0, s0
	s_nop 0
	global_load_lds_dwordx4 v0, s[68:69]
	s_cselect_b32 s0, 0, 0
	v_mul_u32_u24_e32 v0, 0x190, v192
	s_add_i32 s0, s0, 0xc000
	v_add3_u32 v205, v0, s0, v6
	ds_read_b128 v[2:5], v205 offset:0
	ds_read_b128 v[6:9], v205 offset:0x3200
	ds_read_b128 v[44:47], v205 offset:32
	ds_read_b128 v[48:51], v205 offset:0x3220
	ds_read_b128 v[52:55], v205 offset:64
	ds_read_b128 v[56:59], v205 offset:0x3240
	ds_read_b128 v[60:63], v205 offset:0x60
	ds_read_b128 v[64:67], v205 offset:0x3260
	s_nop 0
	s_waitcnt lgkmcnt(6)
	ds_read_b128 v[68:71], v205 offset:0x80
	ds_read_b128 v[72:75], v205 offset:0x3280
	s_waitcnt lgkmcnt(6)
	s_cmp_gt_u32 s82, 62
	v_mfma_f32_32x32x16_bf16 v[18:33], v[2:5], v[172:175], 0
	v_mfma_f32_32x32x16_bf16 v[2:17], v[6:9], v[172:175], 0
	v_mfma_f32_32x32x16_bf16 v[18:33], v[44:47], v[168:171], v[18:33]
	ds_read_b128 v[44:47], v205 offset:0xa0
	v_mfma_f32_32x32x16_bf16 v[2:17], v[48:51], v[168:171], v[2:17]
	ds_read_b128 v[48:51], v205 offset:0x32a0
	s_waitcnt lgkmcnt(6)
	s_nop 0
	v_mfma_f32_32x32x16_bf16 v[18:33], v[52:55], v[164:167], v[18:33]
	ds_read_b128 v[52:55], v205 offset:0xc0
	v_mfma_f32_32x32x16_bf16 v[2:17], v[56:59], v[164:167], v[2:17]
	ds_read_b128 v[56:59], v205 offset:0x32c0
	s_waitcnt lgkmcnt(6)
	s_nop 0
	v_mfma_f32_32x32x16_bf16 v[18:33], v[60:63], v[160:163], v[18:33]
	ds_read_b128 v[60:63], v205 offset:0xe0
	v_mfma_f32_32x32x16_bf16 v[2:17], v[64:67], v[160:163], v[2:17]
	ds_read_b128 v[64:67], v205 offset:0x32e0
	s_waitcnt lgkmcnt(6)
	s_nop 0
	v_mfma_f32_32x32x16_bf16 v[18:33], v[68:71], v[156:159], v[18:33]
	ds_read_b128 v[68:71], v205 offset:0x100
	v_mfma_f32_32x32x16_bf16 v[2:17], v[72:75], v[156:159], v[2:17]
	ds_read_b128 v[72:75], v205 offset:0x3300
	ds_read_b128 v[76:79], v188 offset:0
	s_waitcnt lgkmcnt(7)
	s_nop 0
	v_mfma_f32_32x32x16_bf16 v[18:33], v[44:47], v[152:155], v[18:33]
	ds_read_b128 v[44:47], v205 offset:0x120
	v_mfma_f32_32x32x16_bf16 v[2:17], v[48:51], v[152:155], v[2:17]
	ds_read_b128 v[48:51], v205 offset:0x3320
	ds_read_b128 v[80:83], v188 offset:0x400
	s_waitcnt lgkmcnt(8)
	s_nop 0
	v_mfma_f32_32x32x16_bf16 v[18:33], v[52:55], v[148:151], v[18:33]
	ds_read_b128 v[52:55], v205 offset:0x140
	v_mfma_f32_32x32x16_bf16 v[2:17], v[56:59], v[148:151], v[2:17]
	ds_read_b128 v[56:59], v205 offset:0x3340
	ds_read_b128 v[84:87], v188 offset:0x800
	s_waitcnt lgkmcnt(9)
	s_nop 0
	v_mfma_f32_32x32x16_bf16 v[18:33], v[60:63], v[144:147], v[18:33]
	ds_read_b128 v[60:63], v205 offset:0x160
	v_mfma_f32_32x32x16_bf16 v[2:17], v[64:67], v[144:147], v[2:17]
	ds_read_b128 v[64:67], v205 offset:0x3360
	ds_read_b128 v[88:91], v188 offset:0xc00
	s_waitcnt lgkmcnt(9)
	s_waitcnt lgkmcnt(6)
	s_waitcnt lgkmcnt(3)
	s_nop 0
	s_waitcnt lgkmcnt(0)
	v_mfma_f32_32x32x16_bf16 v[18:33], v[68:71], v[76:79], v[18:33]
	v_mfma_f32_32x32x16_bf16 v[2:17], v[72:75], v[76:79], v[2:17]
	v_mfma_f32_32x32x16_bf16 v[18:33], v[44:47], v[80:83], v[18:33]
	v_mfma_f32_32x32x16_bf16 v[2:17], v[48:51], v[80:83], v[2:17]
	v_mfma_f32_32x32x16_bf16 v[18:33], v[52:55], v[84:87], v[18:33]
	v_mfma_f32_32x32x16_bf16 v[2:17], v[56:59], v[84:87], v[2:17]
	v_mfma_f32_32x32x16_bf16 v[18:33], v[60:63], v[88:91], v[18:33]
	v_mfma_f32_32x32x16_bf16 v[2:17], v[64:67], v[88:91], v[2:17]
	s_cbranch_scc1 .LBB0_616
	v_cmp_gt_i32_e64 s[60:61], 26, v196
	v_cmp_gt_i32_e64 s[62:63], 27, v196
	v_cmp_gt_i32_e64 s[58:59], 25, v196
	s_and_b64 s[60:61], s[62:63], s[60:61]
	v_cmp_gt_i32_e64 s[56:57], 24, v196
	s_and_b64 s[58:59], s[60:61], s[58:59]
	v_cmp_gt_i32_e64 s[54:55], 19, v196
	s_and_b64 s[56:57], s[58:59], s[56:57]
	v_cmp_gt_i32_e64 s[52:53], 18, v196
	s_and_b64 s[54:55], s[56:57], s[54:55]
	v_cmp_gt_i32_e64 s[50:51], 17, v196
	s_and_b64 s[52:53], s[54:55], s[52:53]
	v_cmp_gt_i32_e64 s[48:49], 16, v196
	s_and_b64 s[50:51], s[52:53], s[50:51]
	v_cmp_gt_i32_e64 s[46:47], 11, v196
	s_and_b64 s[48:49], s[50:51], s[48:49]
	v_cmp_gt_i32_e64 s[44:45], 10, v196
	s_and_b64 s[46:47], s[48:49], s[46:47]
	v_cmp_gt_i32_e64 s[42:43], 9, v196
	s_and_b64 s[44:45], s[46:47], s[44:45]
	v_cmp_gt_i32_e64 s[40:41], 8, v196
	s_and_b64 s[42:43], s[44:45], s[42:43]
	v_cmp_gt_i32_e64 s[38:39], 3, v196
	s_and_b64 s[40:41], s[42:43], s[40:41]
	v_cmp_gt_i32_e64 s[36:37], 2, v196
	s_and_b64 s[38:39], s[40:41], s[38:39]
	v_cmp_gt_i32_e64 s[34:35], 1, v196
	s_and_b64 s[36:37], s[38:39], s[36:37]
	v_cmp_gt_i32_e64 s[30:31], 0, v196
	s_and_b64 s[34:35], s[36:37], s[34:35]
	s_and_b64 s[30:31], s[34:35], s[30:31]
	v_cmp_gt_i32_e64 s[28:29], 58, v196
	v_cndmask_b32_e64 v18, v18, v237, s[30:31]
	v_cmp_gt_i32_e64 s[30:31], 59, v196
	v_cmp_gt_i32_e64 s[26:27], 57, v196
	s_and_b64 s[28:29], s[30:31], s[28:29]
	v_cmp_gt_i32_e64 s[24:25], 56, v196
	s_and_b64 s[26:27], s[28:29], s[26:27]
	v_cmp_gt_i32_e64 s[22:23], 51, v196
	s_and_b64 s[24:25], s[26:27], s[24:25]
	v_cmp_gt_i32_e64 s[20:21], 50, v196
	s_and_b64 s[22:23], s[24:25], s[22:23]
	v_cmp_gt_i32_e64 s[18:19], 49, v196
	s_and_b64 s[20:21], s[22:23], s[20:21]
	v_cmp_gt_i32_e64 s[16:17], 48, v196
	s_and_b64 s[18:19], s[20:21], s[18:19]
	v_cmp_gt_i32_e64 s[14:15], 43, v196
	s_and_b64 s[16:17], s[18:19], s[16:17]
	v_cmp_gt_i32_e64 s[12:13], 42, v196
	s_and_b64 s[14:15], s[16:17], s[14:15]
	v_cmp_gt_i32_e64 s[10:11], 41, v196
	s_and_b64 s[12:13], s[14:15], s[12:13]
	v_cmp_gt_i32_e64 s[8:9], 40, v196
	s_and_b64 s[10:11], s[12:13], s[10:11]
	v_cmp_gt_i32_e64 s[6:7], 35, v196
	s_and_b64 s[8:9], s[10:11], s[8:9]
	v_cmp_gt_i32_e64 s[4:5], 34, v196
	s_and_b64 s[6:7], s[8:9], s[6:7]
	v_cmp_gt_i32_e64 s[2:3], 33, v196
	s_and_b64 s[4:5], s[6:7], s[4:5]
	v_cmp_gt_i32_e32 vcc, 32, v196
	s_and_b64 s[2:3], s[4:5], s[2:3]
	s_and_b64 vcc, s[2:3], vcc
	v_cndmask_b32_e64 v33, v33, v237, s[62:63]
	v_cndmask_b32_e64 v32, v32, v237, s[60:61]
	v_cndmask_b32_e64 v31, v31, v237, s[58:59]
	v_cndmask_b32_e64 v30, v30, v237, s[56:57]
	v_cndmask_b32_e64 v29, v29, v237, s[54:55]
	v_cndmask_b32_e64 v28, v28, v237, s[52:53]
	v_cndmask_b32_e64 v27, v27, v237, s[50:51]
	v_cndmask_b32_e64 v26, v26, v237, s[48:49]
	v_cndmask_b32_e64 v25, v25, v237, s[46:47]
	v_cndmask_b32_e64 v24, v24, v237, s[44:45]
	v_cndmask_b32_e64 v23, v23, v237, s[42:43]
	v_cndmask_b32_e64 v22, v22, v237, s[40:41]
	v_cndmask_b32_e64 v21, v21, v237, s[38:39]
	v_cndmask_b32_e64 v20, v20, v237, s[36:37]
	v_cndmask_b32_e64 v19, v19, v237, s[34:35]
	v_cndmask_b32_e64 v17, v17, v237, s[30:31]
	v_cndmask_b32_e64 v16, v16, v237, s[28:29]
	v_cndmask_b32_e64 v15, v15, v237, s[26:27]
	v_cndmask_b32_e64 v14, v14, v237, s[24:25]
	v_cndmask_b32_e64 v13, v13, v237, s[22:23]
	v_cndmask_b32_e64 v12, v12, v237, s[20:21]
	v_cndmask_b32_e64 v11, v11, v237, s[18:19]
	v_cndmask_b32_e64 v10, v10, v237, s[16:17]
	v_cndmask_b32_e64 v9, v9, v237, s[14:15]
	v_cndmask_b32_e64 v8, v8, v237, s[12:13]
	v_cndmask_b32_e64 v7, v7, v237, s[10:11]
	v_cndmask_b32_e64 v6, v6, v237, s[8:9]
	v_cndmask_b32_e64 v5, v5, v237, s[6:7]
	v_cndmask_b32_e64 v4, v4, v237, s[4:5]
	v_cndmask_b32_e64 v3, v3, v237, s[2:3]
	v_cndmask_b32_e32 v2, v2, v237, vcc

.LBB0_799:
	v_readlane_b32 s0, v250, 63
	v_lshlrev_b32_e32 v38, 3, v148
	v_and_b32_e32 v35, 32, v147
	v_add_u32_e32 v7, s0, v147
	v_bfe_u32 v0, v7, 2, 2
	v_lshrrev_b32_e32 v7, 1, v7
	v_and_b32_e32 v37, 8, v7
	v_readlane_b32 s0, v252, 3
	v_and_b32_e32 v36, 24, v38
	v_cndmask_b32_e64 v8, v248, v236, s[4:5]
	v_or3_b32 v7, v0, s0, v37
	v_lshl_or_b32 v7, v7, 11, v35
	v_or3_b32 v7, v7, s72, v36
	v_lshlrev_b32_e32 v7, 1, v7
	v_add_u32_e32 v11, 0x1f700000, v7
	s_mov_b32 m0, s85
	s_nop 0
	global_load_lds_dwordx4 v11, s[68:69]
	v_readlane_b32 s0, v253, 4
	v_add_u32_e32 v12, 0x1f700080, v7
	s_mov_b32 m0, s0
	s_nop 0
	global_load_lds_dwordx4 v12, s[68:69]
	v_readlane_b32 s0, v251, 45
	v_cndmask_b32_e64 v9, v248, v236, s[6:7]
	s_waitcnt vmcnt(2) lgkmcnt(0)
	ds_write_b128 v146, v[40:43]
	ds_write_b128 v146, v[20:23] offset:1024
	ds_write_b128 v146, v[24:27] offset:2048
	ds_write_b128 v146, v[44:47] offset:3072
	s_waitcnt vmcnt(2)
	s_waitcnt lgkmcnt(0)
	s_barrier
	v_add_u32_e32 v6, v6, v8
	s_mov_b32 m0, s0
	s_nop 0
	global_load_lds_dwordx4 v6, s[68:69]
	v_readlane_b32 s0, v252, 9
	v_add_u32_e32 v5, v5, v9
	s_mov_b32 m0, s0
	s_nop 0
	global_load_lds_dwordx4 v5, s[68:69]
	v_readlane_b32 s0, v251, 1
	v_cndmask_b32_e64 v10, v248, v236, s[8:9]
	v_readlane_b32 s1, v251, 2
	v_add_u32_e32 v4, v4, v10
	s_and_b64 vcc, exec, s[0:1]
	v_readlane_b32 s0, v251, 47
	s_mov_b32 m0, s0
	s_nop 0
	global_load_lds_dwordx4 v4, s[68:69]
	s_cbranch_vccnz .LBB0_801
	s_cmp_lg_u32 0, -1
	v_cndmask_b32_e64 v4, v248, v236, s[2:3]
	s_cselect_b32 s0, 0, 0
	v_add_u32_e32 v3, v3, v4
	s_add_i32 s0, s0, 0x18400
	s_mov_b32 m0, s0
	s_nop 0
	global_load_lds_dwordx4 v3, s[68:69]
